# v21 + attention window mask computed as a per-lane range test (3 instructions per score instead of 7)
# speedup vs baseline: 1.0032x; 1.0032x over previous
; #define LAS __attribute__((address_space(3)))
; __device__ __forceinline__ void attn_mfma(LAS unsigned char* lds, int layer, int G, const int wave_s) {
;     ...
;             { const LAS unsigned char* Ks = lds + bf * AT_BUF + kv * 16384;
; #pragma unroll
;               for (int d0 = 0; d0 < 8; ++d0) { const int cb = (d0 * 16 + hi * 8) * 2;
;                   const bf16x8 k0f = *(const LAS bf16x8*)(Ks + AT_KSWZ(r32, cb)), k1f = *(const LAS bf16x8*)(Ks + AT_KSWZ(32 + r32, cb));
;                   p0 = __builtin_amdgcn_mfma_f32_32x32x16_bf16(k0f, qr[d0], p0, 0, 0, 0);
;                   p1 = __builtin_amdgcn_mfma_f32_32x32x16_bf16(k1f, qr[d0], p1, 0, 0, 0); } }
;             if (i < nw) { const int kb = AT_KEY0(i) + 4 * hi - (q0 + r32);
; #pragma unroll
;                 for (int r = 0; r < 16; ++r) { const int d = kb + (r & 3) + 8 * (r >> 2), kk = d + q0 + r32;
;                     if (d < -WINDOW || d > WINDOW || kk < 0) p0[r] = -1.0e30f;
;                     if (d + 32 < -WINDOW || d + 32 > WINDOW || kk + 32 > SEQ - 1 || kk + 32 < 0) p1[r] = -1.0e30f;
;                     if (kk > SEQ - 1) p0[r] = -1.0e30f; } }
.LBB0_796:
	s_and_b32 s71, s17, 0x10000
	v_add_u32_e32 v0, s71, v188
	v_add_u32_e32 v199, v0, v200
	v_add_u32_e32 v222, v0, v202
	v_add_u32_e32 v239, v0, v203
	ds_read_b128 v[66:69], v199
	ds_read_b128 v[82:85], v199 offset:8192
	ds_read_b128 v[240:243], v222
	ds_read_b128 v[218:221], v222 offset:8192
	ds_read_b128 v[248:251], v239
	v_add_u32_e32 v244, v0, v204
	v_add_u32_e32 v246, v0, v205
	v_add_u32_e32 v247, v0, v206
	v_add_u32_e32 v252, v0, v207
	v_add_u32_e32 v171, v0, v208
	s_add_i32 s42, s53, -1
	s_cmp_lt_u32 s42, s25
	s_waitcnt lgkmcnt(4)
	v_mfma_f32_32x32x16_bf16 v[66:81], v[66:69], v[98:101], 0
	s_waitcnt lgkmcnt(3)
	v_mfma_f32_32x32x16_bf16 v[82:97], v[82:85], v[98:101], 0
	s_waitcnt lgkmcnt(2)
	v_mfma_f32_32x32x16_bf16 v[66:81], v[240:243], v[102:105], v[66:81]
	ds_read_b128 v[240:243], v239 offset:8192
	s_waitcnt lgkmcnt(2)
	v_mfma_f32_32x32x16_bf16 v[82:97], v[218:221], v[102:105], v[82:97]
	ds_read_b128 v[218:221], v244
	s_waitcnt lgkmcnt(2)
	v_mfma_f32_32x32x16_bf16 v[66:81], v[248:251], v[106:109], v[66:81]
	ds_read_b128 v[248:251], v244 offset:8192
	s_waitcnt lgkmcnt(2)
	v_mfma_f32_32x32x16_bf16 v[82:97], v[240:243], v[106:109], v[82:97]
	ds_read_b128 v[240:243], v246
	s_waitcnt lgkmcnt(2)
	v_mfma_f32_32x32x16_bf16 v[66:81], v[218:221], v[110:113], v[66:81]
	ds_read_b128 v[218:221], v246 offset:8192
	s_waitcnt lgkmcnt(2)
	v_mfma_f32_32x32x16_bf16 v[82:97], v[248:251], v[110:113], v[82:97]
	ds_read_b128 v[248:251], v247
	s_waitcnt lgkmcnt(2)
	v_mfma_f32_32x32x16_bf16 v[66:81], v[240:243], v[114:117], v[66:81]
	ds_read_b128 v[240:243], v247 offset:8192
	s_waitcnt lgkmcnt(2)
	v_mfma_f32_32x32x16_bf16 v[82:97], v[218:221], v[114:117], v[82:97]
	ds_read_b128 v[218:221], v252
	s_waitcnt lgkmcnt(2)
	v_mfma_f32_32x32x16_bf16 v[66:81], v[248:251], v[118:121], v[66:81]
	ds_read_b128 v[248:251], v252 offset:8192
	s_waitcnt lgkmcnt(2)
	v_mfma_f32_32x32x16_bf16 v[82:97], v[240:243], v[118:121], v[82:97]
	ds_read_b128 v[240:243], v171
	s_waitcnt lgkmcnt(2)
	v_mfma_f32_32x32x16_bf16 v[66:81], v[218:221], v[122:125], v[66:81]
	ds_read_b128 v[218:221], v171 offset:8192
	s_waitcnt lgkmcnt(2)
	v_mfma_f32_32x32x16_bf16 v[82:97], v[248:251], v[122:125], v[82:97]
	s_waitcnt lgkmcnt(1)
	v_mfma_f32_32x32x16_bf16 v[66:81], v[240:243], v[126:129], v[66:81]
	s_waitcnt lgkmcnt(0)
	v_mfma_f32_32x32x16_bf16 v[82:97], v[218:221], v[126:129], v[82:97]
	s_cbranch_scc0 .LBB0_798
	v_add_u32_e32 v218, s68, v214
	v_add_u32_e32 v0, s68, v215
	v_sub_u32_e32 v199, 0, v218
	v_sub_u32_e32 v219, 0x80, v0
	v_max_i32_e32 v199, v199, v219
	v_sub_u32_e32 v218, 0x100, v218
	v_sub_u32_e32 v0, 0x107f, v0
	v_min_i32_e32 v218, v218, v0
	v_sub_u32_e32 v218, v218, v199
	v_mov_b32_e32 v0, 0x100000
	v_cmp_gt_i32_e32 vcc, 0, v218
	s_nop 1
	v_cndmask_b32_e64 v218, v218, 0, vcc
	v_cndmask_b32_e32 v199, v199, v0, vcc
	v_sub_u32_e32 v0, 0, v199
	v_sub_u32_e32 v219, 32, v199
	v_sub_u32_e32 v220, 1, v199
	v_sub_u32_e32 v221, 33, v199
	v_cmp_gt_u32_e64 vcc, v0, v218
	v_cmp_gt_u32_e64 s[42:43], v219, v218
	v_cmp_gt_u32_e64 s[54:55], v220, v218
	v_cmp_gt_u32_e64 s[62:63], v221, v218
	v_cndmask_b32_e64 v66, v66, v238, vcc
	v_cndmask_b32_e64 v82, v82, v238, s[42:43]
	v_cndmask_b32_e64 v67, v67, v238, s[54:55]
	v_cndmask_b32_e64 v83, v83, v238, s[62:63]
	v_sub_u32_e32 v0, 2, v199
	v_sub_u32_e32 v219, 34, v199
	v_sub_u32_e32 v220, 3, v199
	v_sub_u32_e32 v221, 35, v199
	v_cmp_gt_u32_e64 vcc, v0, v218
	v_cmp_gt_u32_e64 s[42:43], v219, v218
	v_cmp_gt_u32_e64 s[54:55], v220, v218
	v_cmp_gt_u32_e64 s[62:63], v221, v218
	v_cndmask_b32_e64 v68, v68, v238, vcc
	v_cndmask_b32_e64 v84, v84, v238, s[42:43]
	v_cndmask_b32_e64 v69, v69, v238, s[54:55]
	v_cndmask_b32_e64 v85, v85, v238, s[62:63]
	v_sub_u32_e32 v0, 8, v199
	v_sub_u32_e32 v219, 40, v199
	v_sub_u32_e32 v220, 9, v199
	v_sub_u32_e32 v221, 41, v199
	v_cmp_gt_u32_e64 vcc, v0, v218
	v_cmp_gt_u32_e64 s[42:43], v219, v218
	v_cmp_gt_u32_e64 s[54:55], v220, v218
	v_cmp_gt_u32_e64 s[62:63], v221, v218
	v_cndmask_b32_e64 v70, v70, v238, vcc
	v_cndmask_b32_e64 v86, v86, v238, s[42:43]
	v_cndmask_b32_e64 v71, v71, v238, s[54:55]
	v_cndmask_b32_e64 v87, v87, v238, s[62:63]
	v_sub_u32_e32 v0, 10, v199
	v_sub_u32_e32 v219, 42, v199
	v_sub_u32_e32 v220, 11, v199
	v_sub_u32_e32 v221, 43, v199
	v_cmp_gt_u32_e64 vcc, v0, v218
	v_cmp_gt_u32_e64 s[42:43], v219, v218
	v_cmp_gt_u32_e64 s[54:55], v220, v218
	v_cmp_gt_u32_e64 s[62:63], v221, v218
	v_cndmask_b32_e64 v72, v72, v238, vcc
	v_cndmask_b32_e64 v88, v88, v238, s[42:43]
	v_cndmask_b32_e64 v73, v73, v238, s[54:55]
	v_cndmask_b32_e64 v89, v89, v238, s[62:63]
	v_sub_u32_e32 v0, 16, v199
	v_sub_u32_e32 v219, 48, v199
	v_sub_u32_e32 v220, 17, v199
	v_sub_u32_e32 v221, 49, v199
	v_cmp_gt_u32_e64 vcc, v0, v218
	v_cmp_gt_u32_e64 s[42:43], v219, v218
	v_cmp_gt_u32_e64 s[54:55], v220, v218
	v_cmp_gt_u32_e64 s[62:63], v221, v218
	v_cndmask_b32_e64 v74, v74, v238, vcc
	v_cndmask_b32_e64 v90, v90, v238, s[42:43]
	v_cndmask_b32_e64 v75, v75, v238, s[54:55]
	v_cndmask_b32_e64 v91, v91, v238, s[62:63]
	v_sub_u32_e32 v0, 18, v199
	v_sub_u32_e32 v219, 50, v199
	v_sub_u32_e32 v220, 19, v199
	v_sub_u32_e32 v221, 51, v199
	v_cmp_gt_u32_e64 vcc, v0, v218
	v_cmp_gt_u32_e64 s[42:43], v219, v218
	v_cmp_gt_u32_e64 s[54:55], v220, v218
	v_cmp_gt_u32_e64 s[62:63], v221, v218
	v_cndmask_b32_e64 v76, v76, v238, vcc
	v_cndmask_b32_e64 v92, v92, v238, s[42:43]
	v_cndmask_b32_e64 v77, v77, v238, s[54:55]
	v_cndmask_b32_e64 v93, v93, v238, s[62:63]
	v_sub_u32_e32 v0, 24, v199
	v_sub_u32_e32 v219, 56, v199
	v_sub_u32_e32 v220, 25, v199
	v_sub_u32_e32 v221, 57, v199
	v_cmp_gt_u32_e64 vcc, v0, v218
	v_cmp_gt_u32_e64 s[42:43], v219, v218
	v_cmp_gt_u32_e64 s[54:55], v220, v218
	v_cmp_gt_u32_e64 s[62:63], v221, v218
	v_cndmask_b32_e64 v78, v78, v238, vcc
	v_cndmask_b32_e64 v94, v94, v238, s[42:43]
	v_cndmask_b32_e64 v79, v79, v238, s[54:55]
	v_cndmask_b32_e64 v95, v95, v238, s[62:63]
	v_sub_u32_e32 v0, 26, v199
	v_sub_u32_e32 v219, 58, v199
	v_sub_u32_e32 v220, 27, v199
	v_sub_u32_e32 v221, 59, v199
	v_cmp_gt_u32_e64 vcc, v0, v218
	v_cmp_gt_u32_e64 s[42:43], v219, v218
	v_cmp_gt_u32_e64 s[54:55], v220, v218
	v_cmp_gt_u32_e64 s[62:63], v221, v218
	v_cndmask_b32_e64 v80, v80, v238, vcc
	v_cndmask_b32_e64 v96, v96, v238, s[42:43]
	v_cndmask_b32_e64 v81, v81, v238, s[54:55]
	v_cndmask_b32_e64 v97, v97, v238, s[62:63]
